# attention loops (sel+MoBA): far-tile constant bias folded into row max / exponent offset (32 fewer VALU), near-tile bias table reads issued before the QK MFMAs, K/V DMA issue moved behind the QK MFMAs
# baseline (speedup 1.0000x reference)
; #define MFMA32(a, b, c) __builtin_amdgcn_mfma_f32_32x32x16_bf16((a), (b), (c), 0, 0, 0)
; #define NEGINF (-__builtin_inff())
; DI int crow(int i, int h) { return (i & 3) + 8 * (i >> 2) + 4 * h; }
; template <class KP, class VP, class ACT, class FILL>
; DI void attn_loop(AttnSt& st, const bf16x8 (&qf)[4], int k0, int k1, size_t vstride, KP kp, VP vp, ACT act, FILL fill) {
;     ...
;   for (int kt = k0; kt <= k1; ++kt) {
;     const int kn = (kt < k1) ? kt + 1 : k1;
;     const int kn2 = (kt + 2 <= k1) ? kt + 2 : k1;
;     {
;       const bf16_t* v0 = vp(kn);
; #pragma unroll
;       for (int j = 0; j < 8; ++j) nxt.v[j] = *(const s16x4*)(v0 + 256 * j);
;     }
;     bf16x8 k2[4];
;     {
;       const bf16_t* krow = kp(kn2);
; #pragma unroll
;       for (int ss = 0; ss < 4; ++ss) k2[ss] = *(const bf16x8*)(krow + 512 * ss);
;     }
;     f32x16 s_next;
; #pragma unroll
;     for (int i = 0; i < 16; ++i) s_next[i] = 0.f;
; #pragma unroll
;     for (int ss = 0; ss < 4; ++ss) s_next = MFMA32(nxt.k[ss], qf[ss], s_next);
; DI void nsa_main_item(const Params& p, int b, int head, int qb, const unsigned char* blut, const float* tbl) {
;     ...
;     attn_loop(st, qf, 0, qb, 32,
;       [&](int kt) { return K + (size_t)kt * 2048 + (h * 32 + r) * 8; },
;       [&](int kt) { return Vt + (size_t)kt * 2048 + (h * 32 + r) * 4; },
;       [&](int kt) { return __ballot((selm >> (kt >> 1)) & 1ull) != 0ull; },
;       [&](int kt, const f32x16& s, float (&lg)[16]) {
;         const bool bs = (selm >> (kt >> 1)) & 1ull;
;         if (qb * 32 - (kt * 32 + 31) >= 1513) {
;           const float b31 = tblh[31];
; #pragma unroll
;           for (int i = 0; i < 16; ++i) lg[i] = bs ? s[i] + b31 : NEGINF;
;         } else {
;           int dist[16]; float bv[16];
; #pragma unroll
;           for (int i = 0; i < 16; ++i) dist[i] = t - (kt * 32 + crow(i, h));
;           bias16(blut, tblh, dist, bv);
; #pragma unroll
;           for (int i = 0; i < 16; ++i) lg[i] = (bs && dist[i] >= 0) ? s[i] + bv[i] : NEGINF;
;         }
.Lasel_loop:
	s_waitcnt vmcnt(2)
	s_barrier
	s_lshr_b32 s23, s56, 1
	s_add_u32 s23, s23, 2
	s_sub_u32 s61, s100, 0x4000
	s_cmp_lt_u32 s61, 0x10000
	s_cselect_b32 s61, 0x18000, s61
	s_mov_b32 s62, s61
	s_cmp_le_u32 s56, s60
	s_cbranch_scc0 .Lasel_skip0
	v_lshl_add_u32 v248, v247, 1, s100
	ds_read_b128 v[96:99], v248 offset:0
	ds_read_b128 v[100:103], v248 offset:1024
	ds_read_b128 v[104:107], v248 offset:2048
	ds_read_b128 v[108:111], v248 offset:3072
	ds_read_b128 v[112:115], v248 offset:4096
	ds_read_b128 v[116:119], v248 offset:5120
	ds_read_b128 v[120:123], v248 offset:6144
	ds_read_b128 v[124:127], v248 offset:7168
	s_sub_i32 s61, s60, s56
	s_cmp_ge_i32 s61, 50
	s_cbranch_scc1 .Lasel_nolut
	s_lshl_b32 s24, s61, 5
	v_add_u32_e32 v241, s24, v221
	v_lshl_add_u32 v244, v241, 2, v242
	v_subrev_u32_e32 v245, 128, v244
	ds_read_b32 v224, v244 offset:108
	ds_read_b32 v225, v244 offset:104
	ds_read_b32 v226, v244 offset:100
	ds_read_b32 v227, v244 offset:96
	ds_read_b32 v228, v244 offset:76
	ds_read_b32 v229, v244 offset:72
	ds_read_b32 v230, v244 offset:68
	ds_read_b32 v231, v244 offset:64
	ds_read_b32 v232, v244 offset:44
	ds_read_b32 v233, v244 offset:40
	ds_read_b32 v234, v244 offset:36
	ds_read_b32 v235, v244 offset:32
	ds_read_b32 v236, v244 offset:12
	ds_read_b32 v237, v244 offset:8
	ds_read_b32 v238, v244 offset:4
	ds_read_b32 v239, v244 offset:0
.Lasel_nolut:
	s_waitcnt lgkmcnt(0)
	v_mfma_f32_32x32x16_bf16 v[32:47], v[96:99], v[80:83], 0
	v_mfma_f32_32x32x16_bf16 v[48:63], v[112:115], v[80:83], 0
	v_mfma_f32_32x32x16_bf16 v[32:47], v[100:103], v[84:87], v[32:47]
	v_mfma_f32_32x32x16_bf16 v[48:63], v[116:119], v[84:87], v[48:63]
	v_mfma_f32_32x32x16_bf16 v[32:47], v[104:107], v[88:91], v[32:47]
	v_mfma_f32_32x32x16_bf16 v[48:63], v[120:123], v[88:91], v[48:63]
	v_mfma_f32_32x32x16_bf16 v[32:47], v[108:111], v[92:95], v[32:47]
	v_mfma_f32_32x32x16_bf16 v[48:63], v[124:127], v[92:95], v[48:63]
	s_lshr_b32 s24, s59, 1
	s_min_u32 s24, s23, s24
	s_lshl_b32 s26, s24, 13
	s_lshl_b32 s24, s58, 10
	s_add_u32 s26, s26, s24
	s_mov_b32 s27, 0
	v_lshl_add_u64 v[248:249], v[148:149], 0, s[26:27]
	v_lshl_add_u64 v[250:251], v[170:171], 0, s[26:27]
	v_add_co_u32_e32 v250, vcc, v250, v247
	v_addc_co_u32_e32 v251, vcc, 0, v251, vcc
	s_add_u32 s24, s24, s62
	s_mov_b32 m0, s24
	s_nop 0
	global_load_lds_dwordx4 v[248:249], off
	s_add_u32 s24, s24, 0x2000
	s_mov_b32 m0, s24
	s_nop 0
	global_load_lds_dwordx4 v[250:251], off
	v_add_u32_e32 v250, s100, v247
	ds_read_b64 v[64:65], v250 offset:8192
	ds_read_b64 v[66:67], v250 offset:8704
	ds_read_b64 v[68:69], v250 offset:9216
	ds_read_b64 v[70:71], v250 offset:9728
	ds_read_b64 v[72:73], v250 offset:10240
	ds_read_b64 v[74:75], v250 offset:10752
	ds_read_b64 v[76:77], v250 offset:11264
	ds_read_b64 v[78:79], v250 offset:11776
	ds_read_b64 v[172:173], v250 offset:12288
	ds_read_b64 v[174:175], v250 offset:12800
	ds_read_b64 v[176:177], v250 offset:13312
	ds_read_b64 v[178:179], v250 offset:13824
	ds_read_b64 v[180:181], v250 offset:14336
	ds_read_b64 v[182:183], v250 offset:14848
	ds_read_b64 v[184:185], v250 offset:15360
	ds_read_b64 v[186:187], v250 offset:15872
	s_lshr_b32 s23, s56, 1
	v_lshrrev_b64 v[248:249], s23, v[168:169]
	v_and_b32_e32 v248, 1, v248
	v_cmp_eq_u32_e64 s[62:63], 1, v248
	s_cmp_ge_i32 s61, 50
	s_cbranch_scc1 .Lasel_far
	s_nop 4
	v_add_f32_e32 v32, v32, v224
	v_add_f32_e32 v33, v33, v225
	v_add_f32_e32 v34, v34, v226
	v_add_f32_e32 v35, v35, v227
	v_add_f32_e32 v36, v36, v228
	v_add_f32_e32 v37, v37, v229
	v_add_f32_e32 v38, v38, v230
	v_add_f32_e32 v39, v39, v231
	v_add_f32_e32 v40, v40, v232
	v_add_f32_e32 v41, v41, v233
	v_add_f32_e32 v42, v42, v234
	v_add_f32_e32 v43, v43, v235
	v_add_f32_e32 v44, v44, v236
	v_add_f32_e32 v45, v45, v237
	v_add_f32_e32 v46, v46, v238
	v_add_f32_e32 v47, v47, v239
	ds_read_b32 v224, v245 offset:108
	ds_read_b32 v225, v245 offset:104
	ds_read_b32 v226, v245 offset:100
	ds_read_b32 v227, v245 offset:96
	ds_read_b32 v228, v245 offset:76
	ds_read_b32 v229, v245 offset:72
	ds_read_b32 v230, v245 offset:68
	ds_read_b32 v231, v245 offset:64
	ds_read_b32 v232, v245 offset:44
	ds_read_b32 v233, v245 offset:40
	ds_read_b32 v234, v245 offset:36
	ds_read_b32 v235, v245 offset:32
	ds_read_b32 v236, v245 offset:12
	ds_read_b32 v237, v245 offset:8
	ds_read_b32 v238, v245 offset:4
	ds_read_b32 v239, v245 offset:0
	s_waitcnt lgkmcnt(8)
	v_add_f32_e32 v48, v48, v224
	v_add_f32_e32 v49, v49, v225
	v_add_f32_e32 v50, v50, v226
	v_add_f32_e32 v51, v51, v227
	v_add_f32_e32 v52, v52, v228
	v_add_f32_e32 v53, v53, v229
	v_add_f32_e32 v54, v54, v230
	v_add_f32_e32 v55, v55, v231
	s_waitcnt lgkmcnt(0)
	v_add_f32_e32 v56, v56, v232
	v_add_f32_e32 v57, v57, v233
	v_add_f32_e32 v58, v58, v234
	v_add_f32_e32 v59, v59, v235
	v_add_f32_e32 v60, v60, v236
	v_add_f32_e32 v61, v61, v237
	v_add_f32_e32 v62, v62, v238
	v_add_f32_e32 v63, v63, v239
	s_cmp_ge_i32 s61, 2
	s_cbranch_scc1 .Lasel_softmax0
; #define NEGINF (-__builtin_inff())
; DI int crow(int i, int h) { return (i & 3) + 8 * (i >> 2) + 4 * h; }
; DI void nsa_main_item(const Params& p, int b, int head, int qb, const unsigned char* blut, const float* tbl) {
;     ...
;       [&](int kt, const f32x16& s, float (&lg)[16]) {
;         const bool bs = (selm >> (kt >> 1)) & 1ull;
;         if (qb * 32 - (kt * 32 + 31) >= 1513) {
;           const float b31 = tblh[31];
; #pragma unroll
;           for (int i = 0; i < 16; ++i) lg[i] = bs ? s[i] + b31 : NEGINF;
;         } else {
;           int dist[16]; float bv[16];
; #pragma unroll
;           for (int i = 0; i < 16; ++i) dist[i] = t - (kt * 32 + crow(i, h));
;           bias16(blut, tblh, dist, bv);
; #pragma unroll
;           for (int i = 0; i < 16; ++i) lg[i] = (bs && dist[i] >= 0) ? s[i] + bv[i] : NEGINF;
;         }
	v_subrev_u32_e32 v246, 32, v241
	v_cmp_le_i32_e32 vcc, 0, v241
	s_nop 1
	v_cndmask_b32_e32 v32, v199, v32, vcc
	v_cmp_le_i32_e32 vcc, 1, v241
	s_nop 1
	v_cndmask_b32_e32 v33, v199, v33, vcc
	v_cmp_le_i32_e32 vcc, 2, v241
	s_nop 1
	v_cndmask_b32_e32 v34, v199, v34, vcc
	v_cmp_le_i32_e32 vcc, 3, v241
	s_nop 1
	v_cndmask_b32_e32 v35, v199, v35, vcc
	v_cmp_le_i32_e32 vcc, 8, v241
	s_nop 1
	v_cndmask_b32_e32 v36, v199, v36, vcc
	v_cmp_le_i32_e32 vcc, 9, v241
	s_nop 1
	v_cndmask_b32_e32 v37, v199, v37, vcc
	v_cmp_le_i32_e32 vcc, 10, v241
	s_nop 1
	v_cndmask_b32_e32 v38, v199, v38, vcc
	v_cmp_le_i32_e32 vcc, 11, v241
	s_nop 1
	v_cndmask_b32_e32 v39, v199, v39, vcc
	v_cmp_le_i32_e32 vcc, 16, v241
	s_nop 1
	v_cndmask_b32_e32 v40, v199, v40, vcc
	v_cmp_le_i32_e32 vcc, 17, v241
	s_nop 1
	v_cndmask_b32_e32 v41, v199, v41, vcc
	v_cmp_le_i32_e32 vcc, 18, v241
	s_nop 1
	v_cndmask_b32_e32 v42, v199, v42, vcc
	v_cmp_le_i32_e32 vcc, 19, v241
	s_nop 1
	v_cndmask_b32_e32 v43, v199, v43, vcc
	v_cmp_le_i32_e32 vcc, 24, v241
	s_nop 1
	v_cndmask_b32_e32 v44, v199, v44, vcc
	v_cmp_le_i32_e32 vcc, 25, v241
	s_nop 1
	v_cndmask_b32_e32 v45, v199, v45, vcc
	v_cmp_le_i32_e32 vcc, 26, v241
	s_nop 1
	v_cndmask_b32_e32 v46, v199, v46, vcc
	v_cmp_le_i32_e32 vcc, 27, v241
	s_nop 1
	v_cndmask_b32_e32 v47, v199, v47, vcc
	v_cmp_le_i32_e32 vcc, 0, v246
	s_nop 1
	v_cndmask_b32_e32 v48, v199, v48, vcc
	v_cmp_le_i32_e32 vcc, 1, v246
	s_nop 1
	v_cndmask_b32_e32 v49, v199, v49, vcc
	v_cmp_le_i32_e32 vcc, 2, v246
	s_nop 1
	v_cndmask_b32_e32 v50, v199, v50, vcc
	v_cmp_le_i32_e32 vcc, 3, v246
	s_nop 1
	v_cndmask_b32_e32 v51, v199, v51, vcc
	v_cmp_le_i32_e32 vcc, 8, v246
	s_nop 1
	v_cndmask_b32_e32 v52, v199, v52, vcc
	v_cmp_le_i32_e32 vcc, 9, v246
	s_nop 1
	v_cndmask_b32_e32 v53, v199, v53, vcc
	v_cmp_le_i32_e32 vcc, 10, v246
	s_nop 1
	v_cndmask_b32_e32 v54, v199, v54, vcc
	v_cmp_le_i32_e32 vcc, 11, v246
	s_nop 1
	v_cndmask_b32_e32 v55, v199, v55, vcc
	v_cmp_le_i32_e32 vcc, 16, v246
	s_nop 1
	v_cndmask_b32_e32 v56, v199, v56, vcc
	v_cmp_le_i32_e32 vcc, 17, v246
	s_nop 1
	v_cndmask_b32_e32 v57, v199, v57, vcc
	v_cmp_le_i32_e32 vcc, 18, v246
	s_nop 1
	v_cndmask_b32_e32 v58, v199, v58, vcc
	v_cmp_le_i32_e32 vcc, 19, v246
	s_nop 1
	v_cndmask_b32_e32 v59, v199, v59, vcc
	v_cmp_le_i32_e32 vcc, 24, v246
	s_nop 1
	v_cndmask_b32_e32 v60, v199, v60, vcc
	v_cmp_le_i32_e32 vcc, 25, v246
	s_nop 1
	v_cndmask_b32_e32 v61, v199, v61, vcc
	v_cmp_le_i32_e32 vcc, 26, v246
	s_nop 1
	v_cndmask_b32_e32 v62, v199, v62, vcc
	v_cmp_le_i32_e32 vcc, 27, v246
	s_nop 1
	v_cndmask_b32_e32 v63, v199, v63, vcc
.Lasel_softmax0:
	v_mov_b32_e32 v246, 0
	s_branch .Lasel_softmax
.Lasel_far:
	v_mov_b32_e32 v246, v240
	s_nop 7
; #define MFMA32(a, b, c) __builtin_amdgcn_mfma_f32_32x32x16_bf16((a), (b), (c), 0, 0, 0)
; #define NEGINF (-__builtin_inff())
; DI float shx32(float v) { const auto r = __builtin_amdgcn_permlane32_swap(__float_as_uint(v), __float_as_uint(v), false, false); return __uint_as_float((threadIdx.x & 32) ? r[0] : r[1]); }
; DI float ex2(float x) { return __builtin_amdgcn_exp2f(x); }
; DI unsigned pack2(float a, float b) { unsigned r; asm("v_cvt_pk_bf16_f32 %0, %1, %2" : "=v"(r) : "v"(a), "v"(b)); return r; }
; DI void softmax_step_r(AttnSt& st, const float (&lg)[16], const KVT& t) {
;   float mx = NEGINF;
; #pragma unroll
;   for (int i = 0; i < 16; ++i) mx = fmaxf(mx, lg[i]);
;   mx = fmaxf(mx, shx32(mx));
;   if (__ballot(mx > NEGINF) == 0ull) return;
;   const float mnew = fmaxf(st.m, mx);
;   const float muse = (mnew == NEGINF) ? 0.f : mnew;
;   const float alpha = ex2(st.m - muse);
;   float pr[16]; float rs = 0.f;
; #pragma unroll
;   for (int i = 0; i < 16; ++i) { pr[i] = ex2(lg[i] - muse); rs += pr[i]; }
;   st.l = st.l * alpha + rs;
;   if (__ballot(mnew != st.m) != 0ull) {
; #pragma unroll
;     for (int i = 0; i < 16; ++i) { st.o0[i] *= alpha; st.o1[i] *= alpha; }
;   }
;   st.m = mnew;
; #pragma unroll
;   for (int s2 = 0; s2 < 2; ++s2) {
;     u32x4 pk; pk.x = pack2(pr[8 * s2], pr[8 * s2 + 1]); pk.y = pack2(pr[8 * s2 + 2], pr[8 * s2 + 3]); pk.z = pack2(pr[8 * s2 + 4], pr[8 * s2 + 5]); pk.w = pack2(pr[8 * s2 + 6], pr[8 * s2 + 7]);
;     const bf16x8 pb = __builtin_bit_cast(bf16x8, pk);
;     const bf16x8 va0 = __builtin_shufflevector(t.v[s2 * 4 + 0], t.v[s2 * 4 + 1], 0, 1, 2, 3, 4, 5, 6, 7);
;     st.o0 = MFMA32(va0, pb, st.o0);
;     const bf16x8 va1 = __builtin_shufflevector(t.v[s2 * 4 + 2], t.v[s2 * 4 + 3], 0, 1, 2, 3, 4, 5, 6, 7);
;     st.o1 = MFMA32(va1, pb, st.o1);
;   }
.Lasel_softmax:
	v_max3_f32 v224, v32, v33, v34
	v_max3_f32 v225, v40, v41, v42
	v_max3_f32 v226, v48, v49, v50
	v_max3_f32 v227, v56, v57, v58
	v_max3_f32 v224, v224, v35, v36
	v_max3_f32 v225, v225, v43, v44
	v_max3_f32 v226, v226, v51, v52
	v_max3_f32 v227, v227, v59, v60
	v_max3_f32 v224, v224, v37, v38
	v_max3_f32 v225, v225, v45, v46
	v_max3_f32 v226, v226, v53, v54
	v_max3_f32 v227, v227, v61, v62
	v_max_f32_e32 v224, v224, v39
	v_max_f32_e32 v225, v225, v47
	v_max_f32_e32 v226, v226, v55
	v_max_f32_e32 v227, v227, v63
	v_max3_f32 v224, v224, v225, v226
	v_max_f32_e32 v224, v224, v227
	v_mov_b32_e32 v225, v224
	v_mov_b32_e32 v226, v224
	s_nop 1
	v_permlane32_swap_b32_e32 v225, v226
	v_cndmask_b32_e64 v225, v225, v226, s[12:13]
	v_max_f32_e32 v224, v224, v225
	v_add_f32_e32 v224, v224, v246
	v_cndmask_b32_e64 v224, v199, v224, s[62:63]
	v_max_f32_e32 v225, v223, v224
	v_cmp_neq_f32_e32 vcc, v199, v225
	s_nop 1
	v_cndmask_b32_e32 v226, 0, v225, vcc
	v_sub_f32_e32 v227, v223, v226
	v_exp_f32_e32 v227, v227
	v_sub_f32_e32 v226, v226, v246
	v_cndmask_b32_e64 v226, v243, v226, s[62:63]
	v_cmp_neq_f32_e32 vcc, v223, v225
	v_mov_b32_e32 v223, v225
	v_sub_f32_e32 v32, v32, v226
	v_sub_f32_e32 v33, v33, v226
	v_sub_f32_e32 v34, v34, v226
	v_sub_f32_e32 v35, v35, v226
	v_sub_f32_e32 v36, v36, v226
	v_sub_f32_e32 v37, v37, v226
	v_sub_f32_e32 v38, v38, v226
	v_sub_f32_e32 v39, v39, v226
	v_sub_f32_e32 v40, v40, v226
	v_sub_f32_e32 v41, v41, v226
	v_sub_f32_e32 v42, v42, v226
	v_sub_f32_e32 v43, v43, v226
	v_sub_f32_e32 v44, v44, v226
	v_sub_f32_e32 v45, v45, v226
	v_sub_f32_e32 v46, v46, v226
	v_sub_f32_e32 v47, v47, v226
	v_sub_f32_e32 v48, v48, v226
	v_sub_f32_e32 v49, v49, v226
	v_sub_f32_e32 v50, v50, v226
	v_sub_f32_e32 v51, v51, v226
	v_sub_f32_e32 v52, v52, v226
	v_sub_f32_e32 v53, v53, v226
	v_sub_f32_e32 v54, v54, v226
	v_sub_f32_e32 v55, v55, v226
	v_sub_f32_e32 v56, v56, v226
	v_sub_f32_e32 v57, v57, v226
	v_sub_f32_e32 v58, v58, v226
	v_sub_f32_e32 v59, v59, v226
	v_sub_f32_e32 v60, v60, v226
	v_sub_f32_e32 v61, v61, v226
	v_sub_f32_e32 v62, v62, v226
	v_sub_f32_e32 v63, v63, v226
	v_exp_f32_e32 v32, v32
	v_exp_f32_e32 v33, v33
	v_exp_f32_e32 v34, v34
	v_exp_f32_e32 v35, v35
	v_exp_f32_e32 v36, v36
	v_exp_f32_e32 v37, v37
	v_exp_f32_e32 v38, v38
	v_exp_f32_e32 v39, v39
	v_exp_f32_e32 v40, v40
	v_exp_f32_e32 v41, v41
	v_exp_f32_e32 v42, v42
	v_exp_f32_e32 v43, v43
	v_exp_f32_e32 v44, v44
	v_exp_f32_e32 v45, v45
	v_exp_f32_e32 v46, v46
	v_exp_f32_e32 v47, v47
	v_exp_f32_e32 v48, v48
	v_exp_f32_e32 v49, v49
	v_exp_f32_e32 v50, v50
	v_exp_f32_e32 v51, v51
	v_exp_f32_e32 v52, v52
	v_exp_f32_e32 v53, v53
	v_exp_f32_e32 v54, v54
	v_exp_f32_e32 v55, v55
	v_exp_f32_e32 v56, v56
	v_exp_f32_e32 v57, v57
	v_exp_f32_e32 v58, v58
	v_exp_f32_e32 v59, v59
	v_exp_f32_e32 v60, v60
	v_exp_f32_e32 v61, v61
	v_exp_f32_e32 v62, v62
	v_exp_f32_e32 v63, v63
	v_add_f32_e32 v228, v32, v33
	v_add_f32_e32 v229, v40, v41
	v_add_f32_e32 v230, v48, v49
	v_add_f32_e32 v231, v56, v57
	v_add_f32_e32 v228, v228, v34
	v_add_f32_e32 v229, v229, v42
	v_add_f32_e32 v230, v230, v50
	v_add_f32_e32 v231, v231, v58
	v_add_f32_e32 v228, v228, v35
	v_add_f32_e32 v229, v229, v43
	v_add_f32_e32 v230, v230, v51
	v_add_f32_e32 v231, v231, v59
	v_add_f32_e32 v228, v228, v36
	v_add_f32_e32 v229, v229, v44
	v_add_f32_e32 v230, v230, v52
	v_add_f32_e32 v231, v231, v60
	v_add_f32_e32 v228, v228, v37
	v_add_f32_e32 v229, v229, v45
	v_add_f32_e32 v230, v230, v53
	v_add_f32_e32 v231, v231, v61
	v_add_f32_e32 v228, v228, v38
	v_add_f32_e32 v229, v229, v46
	v_add_f32_e32 v230, v230, v54
	v_add_f32_e32 v231, v231, v62
	v_add_f32_e32 v228, v228, v39
	v_add_f32_e32 v229, v229, v47
	v_add_f32_e32 v230, v230, v55
	v_add_f32_e32 v231, v231, v63
	v_add_f32_e32 v228, v228, v229
	v_add_f32_e32 v230, v230, v231
	v_add_f32_e32 v228, v228, v230
	v_fma_f32 v222, v222, v227, v228
	s_cbranch_vccz .Lasel_noscale
	v_mul_f32_e32 v0, v227, v0
	v_mul_f32_e32 v1, v227, v1
	v_mul_f32_e32 v2, v227, v2
	v_mul_f32_e32 v3, v227, v3
	v_mul_f32_e32 v4, v227, v4
	v_mul_f32_e32 v5, v227, v5
	v_mul_f32_e32 v6, v227, v6
	v_mul_f32_e32 v7, v227, v7
	v_mul_f32_e32 v8, v227, v8
	v_mul_f32_e32 v9, v227, v9
	v_mul_f32_e32 v10, v227, v10
	v_mul_f32_e32 v11, v227, v11
	v_mul_f32_e32 v12, v227, v12
	v_mul_f32_e32 v13, v227, v13
	v_mul_f32_e32 v14, v227, v14
	v_mul_f32_e32 v15, v227, v15
	v_mul_f32_e32 v16, v227, v16
	v_mul_f32_e32 v17, v227, v17
	v_mul_f32_e32 v18, v227, v18
	v_mul_f32_e32 v19, v227, v19
	v_mul_f32_e32 v20, v227, v20
	v_mul_f32_e32 v21, v227, v21
	v_mul_f32_e32 v22, v227, v22
	v_mul_f32_e32 v23, v227, v23
	v_mul_f32_e32 v24, v227, v24
	v_mul_f32_e32 v25, v227, v25
	v_mul_f32_e32 v26, v227, v26
	v_mul_f32_e32 v27, v227, v27
	v_mul_f32_e32 v28, v227, v28
	v_mul_f32_e32 v29, v227, v29
	v_mul_f32_e32 v30, v227, v30
	v_mul_f32_e32 v31, v227, v31
.Lasel_noscale:
	v_cvt_pk_bf16_f32 v224, v32, v33
	v_cvt_pk_bf16_f32 v225, v34, v35
	v_cvt_pk_bf16_f32 v226, v36, v37
	v_cvt_pk_bf16_f32 v227, v38, v39
	v_cvt_pk_bf16_f32 v228, v40, v41
	v_cvt_pk_bf16_f32 v229, v42, v43
	v_cvt_pk_bf16_f32 v230, v44, v45
	v_cvt_pk_bf16_f32 v231, v46, v47
	v_cvt_pk_bf16_f32 v232, v48, v49
	v_cvt_pk_bf16_f32 v233, v50, v51
	v_cvt_pk_bf16_f32 v234, v52, v53
	v_cvt_pk_bf16_f32 v235, v54, v55
	v_cvt_pk_bf16_f32 v236, v56, v57
	v_cvt_pk_bf16_f32 v237, v58, v59
	v_cvt_pk_bf16_f32 v238, v60, v61
	v_cvt_pk_bf16_f32 v239, v62, v63
	s_waitcnt lgkmcnt(0)
	s_nop 1
	v_mfma_f32_32x32x16_bf16 v[0:15], v[64:67], v[224:227], v[0:15]
	v_mfma_f32_32x32x16_bf16 v[16:31], v[68:71], v[224:227], v[16:31]
	v_mfma_f32_32x32x16_bf16 v[0:15], v[72:75], v[228:231], v[0:15]
	v_mfma_f32_32x32x16_bf16 v[16:31], v[76:79], v[228:231], v[16:31]
	v_mfma_f32_32x32x16_bf16 v[0:15], v[172:175], v[232:235], v[0:15]
	v_mfma_f32_32x32x16_bf16 v[16:31], v[176:179], v[232:235], v[16:31]
	v_mfma_f32_32x32x16_bf16 v[0:15], v[180:183], v[236:239], v[0:15]
	v_mfma_f32_32x32x16_bf16 v[16:31], v[184:187], v[236:239], v[16:31]
	s_branch .Lasel_skip
.Lasel_skip0:
	s_lshr_b32 s24, s59, 1
	s_min_u32 s24, s23, s24
	s_lshl_b32 s26, s24, 13
	s_lshl_b32 s24, s58, 10
	s_add_u32 s26, s26, s24
	s_mov_b32 s27, 0
	v_lshl_add_u64 v[248:249], v[148:149], 0, s[26:27]
	v_lshl_add_u64 v[250:251], v[170:171], 0, s[26:27]
	v_add_co_u32_e32 v250, vcc, v250, v247
	v_addc_co_u32_e32 v251, vcc, 0, v251, vcc
	s_add_u32 s24, s24, s62
	s_mov_b32 m0, s24
	s_nop 0
	global_load_lds_dwordx4 v[248:249], off
	s_add_u32 s24, s24, 0x2000
	s_mov_b32 m0, s24
	s_nop 0
	global_load_lds_dwordx4 v[250:251], off

; #define MFMA32(a, b, c) __builtin_amdgcn_mfma_f32_32x32x16_bf16((a), (b), (c), 0, 0, 0)
; #define NEGINF (-__builtin_inff())
; DI int crow(int i, int h) { return (i & 3) + 8 * (i >> 2) + 4 * h; }
; template <class KP, class VP, class ACT, class FILL>
; DI void attn_loop(AttnSt& st, const bf16x8 (&qf)[4], int k0, int k1, size_t vstride, KP kp, VP vp, ACT act, FILL fill) {
;     ...
;   for (int kt = k0; kt <= k1; ++kt) {
;     const int kn = (kt < k1) ? kt + 1 : k1;
;     const int kn2 = (kt + 2 <= k1) ? kt + 2 : k1;
;     {
;       const bf16_t* v0 = vp(kn);
; #pragma unroll
;       for (int j = 0; j < 8; ++j) nxt.v[j] = *(const s16x4*)(v0 + 256 * j);
;     }
;     bf16x8 k2[4];
;     {
;       const bf16_t* krow = kp(kn2);
; #pragma unroll
;       for (int ss = 0; ss < 4; ++ss) k2[ss] = *(const bf16x8*)(krow + 512 * ss);
;     }
;     f32x16 s_next;
; #pragma unroll
;     for (int i = 0; i < 16; ++i) s_next[i] = 0.f;
; #pragma unroll
;     for (int ss = 0; ss < 4; ++ss) s_next = MFMA32(nxt.k[ss], qf[ss], s_next);
; DI void moba_item(const Params& p, int b, int hd, int qb, const unsigned char* blut, const float* tbl) {
;     ...
;   attn_loop(st, qf, 0, qb, 32,
;     [&](int kt) { return K + (size_t)kt * 2048 + (h * 32 + r) * 8; },
;     [&](int kt) { return Vt + (size_t)kt * 2048 + (h * 32 + r) * 4; },
;     [&](int kt) { return __ballot((mmask >> (kt >> 3)) & 1u) != 0ull; },
;     [&](int kt, const f32x16& s, float (&lg)[16]) {
;       const bool bs = (mmask >> (kt >> 3)) & 1u;
;       if (qb * 32 - (kt * 32 + 31) >= 1513) {
;         const float b31 = tblh[31];
; #pragma unroll
;         for (int i = 0; i < 16; ++i) lg[i] = bs ? s[i] + b31 : NEGINF;
;       } else {
;         int dist[16]; float bv[16];
; #pragma unroll
;         for (int i = 0; i < 16; ++i) dist[i] = t - (kt * 32 + crow(i, h));
;         bias16(blut, tblh, dist, bv);
; #pragma unroll
;         for (int i = 0; i < 16; ++i) lg[i] = (bs && dist[i] >= 0) ? s[i] + bv[i] : NEGINF;
;       }
;     });
.Lamoba_loop:
	s_waitcnt vmcnt(2)
	s_barrier
	s_lshr_b32 s23, s56, 1
	s_add_u32 s23, s23, 2
	s_sub_u32 s61, s100, 0x4000
	s_cmp_lt_u32 s61, 0x10000
	s_cselect_b32 s61, 0x18000, s61
	s_mov_b32 s62, s61
	s_cmp_le_u32 s56, s60
	s_cbranch_scc0 .Lamoba_skip0
	v_lshl_add_u32 v186, v185, 1, s100
	ds_read_b128 v[96:99], v186 offset:0
	ds_read_b128 v[100:103], v186 offset:1024
	ds_read_b128 v[104:107], v186 offset:2048
	ds_read_b128 v[108:111], v186 offset:3072
	ds_read_b128 v[112:115], v186 offset:4096
	ds_read_b128 v[116:119], v186 offset:5120
	ds_read_b128 v[120:123], v186 offset:6144
	ds_read_b128 v[124:127], v186 offset:7168
	s_sub_i32 s61, s60, s56
	s_cmp_ge_i32 s61, 50
	s_cbranch_scc1 .Lamoba_nolut
	s_lshl_b32 s24, s61, 5
	v_add_u32_e32 v179, s24, v158
	v_lshl_add_u32 v182, v179, 2, v180
	v_subrev_u32_e32 v183, 128, v182
	ds_read_b32 v162, v182 offset:108
	ds_read_b32 v163, v182 offset:104
	ds_read_b32 v164, v182 offset:100
	ds_read_b32 v165, v182 offset:96
	ds_read_b32 v166, v182 offset:76
	ds_read_b32 v167, v182 offset:72
	ds_read_b32 v168, v182 offset:68
	ds_read_b32 v169, v182 offset:64
	ds_read_b32 v170, v182 offset:44
	ds_read_b32 v171, v182 offset:40
	ds_read_b32 v172, v182 offset:36
	ds_read_b32 v173, v182 offset:32
	ds_read_b32 v174, v182 offset:12
	ds_read_b32 v175, v182 offset:8
	ds_read_b32 v176, v182 offset:4
	ds_read_b32 v177, v182 offset:0
.Lamoba_nolut:
	s_waitcnt lgkmcnt(0)
	v_mfma_f32_32x32x16_bf16 v[32:47], v[96:99], v[80:83], 0
	v_mfma_f32_32x32x16_bf16 v[48:63], v[112:115], v[80:83], 0
	v_mfma_f32_32x32x16_bf16 v[32:47], v[100:103], v[84:87], v[32:47]
	v_mfma_f32_32x32x16_bf16 v[48:63], v[116:119], v[84:87], v[48:63]
	v_mfma_f32_32x32x16_bf16 v[32:47], v[104:107], v[88:91], v[32:47]
	v_mfma_f32_32x32x16_bf16 v[48:63], v[120:123], v[88:91], v[48:63]
	v_mfma_f32_32x32x16_bf16 v[32:47], v[108:111], v[92:95], v[32:47]
	v_mfma_f32_32x32x16_bf16 v[48:63], v[124:127], v[92:95], v[48:63]
	s_lshr_b32 s24, s59, 1
	s_min_u32 s24, s23, s24
	s_lshl_b32 s26, s24, 13
	s_lshl_b32 s24, s58, 10
	s_add_u32 s26, s26, s24
	s_mov_b32 s27, 0
	v_lshl_add_u64 v[186:187], v[134:135], 0, s[26:27]
	v_lshl_add_u64 v[218:219], v[136:137], 0, s[26:27]
	v_add_co_u32_e32 v218, vcc, v218, v185
	v_addc_co_u32_e32 v219, vcc, 0, v219, vcc
	s_add_u32 s24, s24, s62
	s_mov_b32 m0, s24
	s_nop 0
	global_load_lds_dwordx4 v[186:187], off
	s_add_u32 s24, s24, 0x2000
	s_mov_b32 m0, s24
	s_nop 0
	global_load_lds_dwordx4 v[218:219], off
	v_add_u32_e32 v218, s100, v185
	ds_read_b64 v[64:65], v218 offset:8192
	ds_read_b64 v[66:67], v218 offset:8704
	ds_read_b64 v[68:69], v218 offset:9216
	ds_read_b64 v[70:71], v218 offset:9728
	ds_read_b64 v[72:73], v218 offset:10240
	ds_read_b64 v[74:75], v218 offset:10752
	ds_read_b64 v[76:77], v218 offset:11264
	ds_read_b64 v[78:79], v218 offset:11776
	ds_read_b64 v[138:139], v218 offset:12288
	ds_read_b64 v[140:141], v218 offset:12800
	ds_read_b64 v[142:143], v218 offset:13312
	ds_read_b64 v[144:145], v218 offset:13824
	ds_read_b64 v[146:147], v218 offset:14336
	ds_read_b64 v[148:149], v218 offset:14848
	ds_read_b64 v[150:151], v218 offset:15360
	ds_read_b64 v[152:153], v218 offset:15872
	s_lshr_b32 s23, s56, 3
	v_bfe_u32 v184, v157, s23, 1
	v_cmp_eq_u32_e64 s[62:63], 1, v184
	s_cmp_ge_i32 s61, 50
	s_cbranch_scc1 .Lamoba_far
	s_nop 4
	v_add_f32_e32 v32, v32, v162
	v_add_f32_e32 v33, v33, v163
	v_add_f32_e32 v34, v34, v164
	v_add_f32_e32 v35, v35, v165
	v_add_f32_e32 v36, v36, v166
	v_add_f32_e32 v37, v37, v167
	v_add_f32_e32 v38, v38, v168
	v_add_f32_e32 v39, v39, v169
	v_add_f32_e32 v40, v40, v170
	v_add_f32_e32 v41, v41, v171
	v_add_f32_e32 v42, v42, v172
	v_add_f32_e32 v43, v43, v173
	v_add_f32_e32 v44, v44, v174
	v_add_f32_e32 v45, v45, v175
	v_add_f32_e32 v46, v46, v176
	v_add_f32_e32 v47, v47, v177
	ds_read_b32 v162, v183 offset:108
	ds_read_b32 v163, v183 offset:104
	ds_read_b32 v164, v183 offset:100
	ds_read_b32 v165, v183 offset:96
	ds_read_b32 v166, v183 offset:76
	ds_read_b32 v167, v183 offset:72
	ds_read_b32 v168, v183 offset:68
	ds_read_b32 v169, v183 offset:64
	ds_read_b32 v170, v183 offset:44
	ds_read_b32 v171, v183 offset:40
	ds_read_b32 v172, v183 offset:36
	ds_read_b32 v173, v183 offset:32
	ds_read_b32 v174, v183 offset:12
	ds_read_b32 v175, v183 offset:8
	ds_read_b32 v176, v183 offset:4
	ds_read_b32 v177, v183 offset:0
	s_waitcnt lgkmcnt(8)
	v_add_f32_e32 v48, v48, v162
	v_add_f32_e32 v49, v49, v163
	v_add_f32_e32 v50, v50, v164
	v_add_f32_e32 v51, v51, v165
	v_add_f32_e32 v52, v52, v166
	v_add_f32_e32 v53, v53, v167
	v_add_f32_e32 v54, v54, v168
	v_add_f32_e32 v55, v55, v169
	s_waitcnt lgkmcnt(0)
	v_add_f32_e32 v56, v56, v170
	v_add_f32_e32 v57, v57, v171
	v_add_f32_e32 v58, v58, v172
	v_add_f32_e32 v59, v59, v173
	v_add_f32_e32 v60, v60, v174
	v_add_f32_e32 v61, v61, v175
	v_add_f32_e32 v62, v62, v176
	v_add_f32_e32 v63, v63, v177
	s_cmp_ge_i32 s61, 2
	s_cbranch_scc1 .Lamoba_softmax0
; #define NEGINF (-__builtin_inff())
; DI int crow(int i, int h) { return (i & 3) + 8 * (i >> 2) + 4 * h; }
; DI void moba_item(const Params& p, int b, int hd, int qb, const unsigned char* blut, const float* tbl) {
;     ...
;     [&](int kt, const f32x16& s, float (&lg)[16]) {
;       const bool bs = (mmask >> (kt >> 3)) & 1u;
;       if (qb * 32 - (kt * 32 + 31) >= 1513) {
;         const float b31 = tblh[31];
; #pragma unroll
;         for (int i = 0; i < 16; ++i) lg[i] = bs ? s[i] + b31 : NEGINF;
;       } else {
;         int dist[16]; float bv[16];
; #pragma unroll
;         for (int i = 0; i < 16; ++i) dist[i] = t - (kt * 32 + crow(i, h));
;         bias16(blut, tblh, dist, bv);
; #pragma unroll
;         for (int i = 0; i < 16; ++i) lg[i] = (bs && dist[i] >= 0) ? s[i] + bv[i] : NEGINF;
;       }
	v_subrev_u32_e32 v184, 32, v179
	v_cmp_le_i32_e32 vcc, 0, v179
	s_nop 1
	v_cndmask_b32_e32 v32, v199, v32, vcc
	v_cmp_le_i32_e32 vcc, 1, v179
	s_nop 1
	v_cndmask_b32_e32 v33, v199, v33, vcc
	v_cmp_le_i32_e32 vcc, 2, v179
	s_nop 1
	v_cndmask_b32_e32 v34, v199, v34, vcc
	v_cmp_le_i32_e32 vcc, 3, v179
	s_nop 1
	v_cndmask_b32_e32 v35, v199, v35, vcc
	v_cmp_le_i32_e32 vcc, 8, v179
	s_nop 1
	v_cndmask_b32_e32 v36, v199, v36, vcc
	v_cmp_le_i32_e32 vcc, 9, v179
	s_nop 1
	v_cndmask_b32_e32 v37, v199, v37, vcc
	v_cmp_le_i32_e32 vcc, 10, v179
	s_nop 1
	v_cndmask_b32_e32 v38, v199, v38, vcc
	v_cmp_le_i32_e32 vcc, 11, v179
	s_nop 1
	v_cndmask_b32_e32 v39, v199, v39, vcc
	v_cmp_le_i32_e32 vcc, 16, v179
	s_nop 1
	v_cndmask_b32_e32 v40, v199, v40, vcc
	v_cmp_le_i32_e32 vcc, 17, v179
	s_nop 1
	v_cndmask_b32_e32 v41, v199, v41, vcc
	v_cmp_le_i32_e32 vcc, 18, v179
	s_nop 1
	v_cndmask_b32_e32 v42, v199, v42, vcc
	v_cmp_le_i32_e32 vcc, 19, v179
	s_nop 1
	v_cndmask_b32_e32 v43, v199, v43, vcc
	v_cmp_le_i32_e32 vcc, 24, v179
	s_nop 1
	v_cndmask_b32_e32 v44, v199, v44, vcc
	v_cmp_le_i32_e32 vcc, 25, v179
	s_nop 1
	v_cndmask_b32_e32 v45, v199, v45, vcc
	v_cmp_le_i32_e32 vcc, 26, v179
	s_nop 1
	v_cndmask_b32_e32 v46, v199, v46, vcc
	v_cmp_le_i32_e32 vcc, 27, v179
	s_nop 1
	v_cndmask_b32_e32 v47, v199, v47, vcc
	v_cmp_le_i32_e32 vcc, 0, v184
	s_nop 1
	v_cndmask_b32_e32 v48, v199, v48, vcc
	v_cmp_le_i32_e32 vcc, 1, v184
	s_nop 1
	v_cndmask_b32_e32 v49, v199, v49, vcc
	v_cmp_le_i32_e32 vcc, 2, v184
	s_nop 1
	v_cndmask_b32_e32 v50, v199, v50, vcc
	v_cmp_le_i32_e32 vcc, 3, v184
	s_nop 1
	v_cndmask_b32_e32 v51, v199, v51, vcc
	v_cmp_le_i32_e32 vcc, 8, v184
	s_nop 1
	v_cndmask_b32_e32 v52, v199, v52, vcc
	v_cmp_le_i32_e32 vcc, 9, v184
	s_nop 1
	v_cndmask_b32_e32 v53, v199, v53, vcc
	v_cmp_le_i32_e32 vcc, 10, v184
	s_nop 1
	v_cndmask_b32_e32 v54, v199, v54, vcc
	v_cmp_le_i32_e32 vcc, 11, v184
	s_nop 1
	v_cndmask_b32_e32 v55, v199, v55, vcc
	v_cmp_le_i32_e32 vcc, 16, v184
	s_nop 1
	v_cndmask_b32_e32 v56, v199, v56, vcc
	v_cmp_le_i32_e32 vcc, 17, v184
	s_nop 1
	v_cndmask_b32_e32 v57, v199, v57, vcc
	v_cmp_le_i32_e32 vcc, 18, v184
	s_nop 1
	v_cndmask_b32_e32 v58, v199, v58, vcc
	v_cmp_le_i32_e32 vcc, 19, v184
	s_nop 1
	v_cndmask_b32_e32 v59, v199, v59, vcc
	v_cmp_le_i32_e32 vcc, 24, v184
	s_nop 1
	v_cndmask_b32_e32 v60, v199, v60, vcc
	v_cmp_le_i32_e32 vcc, 25, v184
	s_nop 1
	v_cndmask_b32_e32 v61, v199, v61, vcc
	v_cmp_le_i32_e32 vcc, 26, v184
	s_nop 1
	v_cndmask_b32_e32 v62, v199, v62, vcc
	v_cmp_le_i32_e32 vcc, 27, v184
	s_nop 1
	v_cndmask_b32_e32 v63, v199, v63, vcc
.Lamoba_softmax0:
	v_mov_b32_e32 v184, 0
	s_branch .Lamoba_softmax
.Lamoba_far:
	v_mov_b32_e32 v184, v178
	s_nop 7
; #define MFMA32(a, b, c) __builtin_amdgcn_mfma_f32_32x32x16_bf16((a), (b), (c), 0, 0, 0)
; #define NEGINF (-__builtin_inff())
; DI float shx32(float v) { const auto r = __builtin_amdgcn_permlane32_swap(__float_as_uint(v), __float_as_uint(v), false, false); return __uint_as_float((threadIdx.x & 32) ? r[0] : r[1]); }
; DI float ex2(float x) { return __builtin_amdgcn_exp2f(x); }
; DI unsigned pack2(float a, float b) { unsigned r; asm("v_cvt_pk_bf16_f32 %0, %1, %2" : "=v"(r) : "v"(a), "v"(b)); return r; }
; DI void softmax_step_r(AttnSt& st, const float (&lg)[16], const KVT& t) {
;   float mx = NEGINF;
; #pragma unroll
;   for (int i = 0; i < 16; ++i) mx = fmaxf(mx, lg[i]);
;   mx = fmaxf(mx, shx32(mx));
;   if (__ballot(mx > NEGINF) == 0ull) return;
;   const float mnew = fmaxf(st.m, mx);
;   const float muse = (mnew == NEGINF) ? 0.f : mnew;
;   const float alpha = ex2(st.m - muse);
;   float pr[16]; float rs = 0.f;
; #pragma unroll
;   for (int i = 0; i < 16; ++i) { pr[i] = ex2(lg[i] - muse); rs += pr[i]; }
;   st.l = st.l * alpha + rs;
;   if (__ballot(mnew != st.m) != 0ull) {
; #pragma unroll
;     for (int i = 0; i < 16; ++i) { st.o0[i] *= alpha; st.o1[i] *= alpha; }
;   }
;   st.m = mnew;
; #pragma unroll
;   for (int s2 = 0; s2 < 2; ++s2) {
;     u32x4 pk; pk.x = pack2(pr[8 * s2], pr[8 * s2 + 1]); pk.y = pack2(pr[8 * s2 + 2], pr[8 * s2 + 3]); pk.z = pack2(pr[8 * s2 + 4], pr[8 * s2 + 5]); pk.w = pack2(pr[8 * s2 + 6], pr[8 * s2 + 7]);
;     const bf16x8 pb = __builtin_bit_cast(bf16x8, pk);
;     const bf16x8 va0 = __builtin_shufflevector(t.v[s2 * 4 + 0], t.v[s2 * 4 + 1], 0, 1, 2, 3, 4, 5, 6, 7);
;     st.o0 = MFMA32(va0, pb, st.o0);
;     const bf16x8 va1 = __builtin_shufflevector(t.v[s2 * 4 + 2], t.v[s2 * 4 + 3], 0, 1, 2, 3, 4, 5, 6, 7);
;     st.o1 = MFMA32(va1, pb, st.o1);
;   }
.Lamoba_softmax:
	v_max3_f32 v162, v32, v33, v34
	v_max3_f32 v163, v40, v41, v42
	v_max3_f32 v164, v48, v49, v50
	v_max3_f32 v165, v56, v57, v58
	v_max3_f32 v162, v162, v35, v36
	v_max3_f32 v163, v163, v43, v44
	v_max3_f32 v164, v164, v51, v52
	v_max3_f32 v165, v165, v59, v60
	v_max3_f32 v162, v162, v37, v38
	v_max3_f32 v163, v163, v45, v46
	v_max3_f32 v164, v164, v53, v54
	v_max3_f32 v165, v165, v61, v62
	v_max_f32_e32 v162, v162, v39
	v_max_f32_e32 v163, v163, v47
	v_max_f32_e32 v164, v164, v55
	v_max_f32_e32 v165, v165, v63
	v_max3_f32 v162, v162, v163, v164
	v_max_f32_e32 v162, v162, v165
	v_mov_b32_e32 v163, v162
	v_mov_b32_e32 v164, v162
	s_nop 1
	v_permlane32_swap_b32_e32 v163, v164
	v_cndmask_b32_e64 v163, v163, v164, s[12:13]
	v_max_f32_e32 v162, v162, v163
	v_add_f32_e32 v162, v162, v184
	v_cndmask_b32_e64 v162, v199, v162, s[62:63]
	v_max_f32_e32 v163, v161, v162
	v_cmp_neq_f32_e32 vcc, v199, v163
	s_nop 1
	v_cndmask_b32_e32 v164, 0, v163, vcc
	v_sub_f32_e32 v165, v161, v164
	v_exp_f32_e32 v165, v165
	v_sub_f32_e32 v164, v164, v184
	v_cndmask_b32_e64 v164, v181, v164, s[62:63]
	v_cmp_neq_f32_e32 vcc, v161, v163
	v_mov_b32_e32 v161, v163
	v_sub_f32_e32 v32, v32, v164
	v_sub_f32_e32 v33, v33, v164
	v_sub_f32_e32 v34, v34, v164
	v_sub_f32_e32 v35, v35, v164
	v_sub_f32_e32 v36, v36, v164
	v_sub_f32_e32 v37, v37, v164
	v_sub_f32_e32 v38, v38, v164
	v_sub_f32_e32 v39, v39, v164
	v_sub_f32_e32 v40, v40, v164
	v_sub_f32_e32 v41, v41, v164
	v_sub_f32_e32 v42, v42, v164
	v_sub_f32_e32 v43, v43, v164
	v_sub_f32_e32 v44, v44, v164
	v_sub_f32_e32 v45, v45, v164
	v_sub_f32_e32 v46, v46, v164
	v_sub_f32_e32 v47, v47, v164
	v_sub_f32_e32 v48, v48, v164
	v_sub_f32_e32 v49, v49, v164
	v_sub_f32_e32 v50, v50, v164
	v_sub_f32_e32 v51, v51, v164
	v_sub_f32_e32 v52, v52, v164
	v_sub_f32_e32 v53, v53, v164
	v_sub_f32_e32 v54, v54, v164
	v_sub_f32_e32 v55, v55, v164
	v_sub_f32_e32 v56, v56, v164
	v_sub_f32_e32 v57, v57, v164
	v_sub_f32_e32 v58, v58, v164
	v_sub_f32_e32 v59, v59, v164
	v_sub_f32_e32 v60, v60, v164
	v_sub_f32_e32 v61, v61, v164
	v_sub_f32_e32 v62, v62, v164
	v_sub_f32_e32 v63, v63, v164
	v_exp_f32_e32 v32, v32
	v_exp_f32_e32 v33, v33
	v_exp_f32_e32 v34, v34
	v_exp_f32_e32 v35, v35
	v_exp_f32_e32 v36, v36
	v_exp_f32_e32 v37, v37
	v_exp_f32_e32 v38, v38
	v_exp_f32_e32 v39, v39
	v_exp_f32_e32 v40, v40
	v_exp_f32_e32 v41, v41
	v_exp_f32_e32 v42, v42
	v_exp_f32_e32 v43, v43
	v_exp_f32_e32 v44, v44
	v_exp_f32_e32 v45, v45
	v_exp_f32_e32 v46, v46
	v_exp_f32_e32 v47, v47
	v_exp_f32_e32 v48, v48
	v_exp_f32_e32 v49, v49
	v_exp_f32_e32 v50, v50
	v_exp_f32_e32 v51, v51
	v_exp_f32_e32 v52, v52
	v_exp_f32_e32 v53, v53
	v_exp_f32_e32 v54, v54
	v_exp_f32_e32 v55, v55
	v_exp_f32_e32 v56, v56
	v_exp_f32_e32 v57, v57
	v_exp_f32_e32 v58, v58
	v_exp_f32_e32 v59, v59
	v_exp_f32_e32 v60, v60
	v_exp_f32_e32 v61, v61
	v_exp_f32_e32 v62, v62
	v_exp_f32_e32 v63, v63
	v_add_f32_e32 v166, v32, v33
	v_add_f32_e32 v167, v40, v41
	v_add_f32_e32 v168, v48, v49
	v_add_f32_e32 v169, v56, v57
	v_add_f32_e32 v166, v166, v34
	v_add_f32_e32 v167, v167, v42
	v_add_f32_e32 v168, v168, v50
	v_add_f32_e32 v169, v169, v58
	v_add_f32_e32 v166, v166, v35
	v_add_f32_e32 v167, v167, v43
	v_add_f32_e32 v168, v168, v51
	v_add_f32_e32 v169, v169, v59
	v_add_f32_e32 v166, v166, v36
	v_add_f32_e32 v167, v167, v44
	v_add_f32_e32 v168, v168, v52
	v_add_f32_e32 v169, v169, v60
	v_add_f32_e32 v166, v166, v37
	v_add_f32_e32 v167, v167, v45
	v_add_f32_e32 v168, v168, v53
	v_add_f32_e32 v169, v169, v61
	v_add_f32_e32 v166, v166, v38
	v_add_f32_e32 v167, v167, v46
	v_add_f32_e32 v168, v168, v54
	v_add_f32_e32 v169, v169, v62
	v_add_f32_e32 v166, v166, v39
	v_add_f32_e32 v167, v167, v47
	v_add_f32_e32 v168, v168, v55
	v_add_f32_e32 v169, v169, v63
	v_add_f32_e32 v166, v166, v167
	v_add_f32_e32 v168, v168, v169
	v_add_f32_e32 v166, v166, v168
	v_fma_f32 v160, v160, v165, v166
	s_cbranch_vccz .Lamoba_noscale
	v_mul_f32_e32 v0, v165, v0
	v_mul_f32_e32 v1, v165, v1
	v_mul_f32_e32 v2, v165, v2
	v_mul_f32_e32 v3, v165, v3
	v_mul_f32_e32 v4, v165, v4
	v_mul_f32_e32 v5, v165, v5
	v_mul_f32_e32 v6, v165, v6
	v_mul_f32_e32 v7, v165, v7
	v_mul_f32_e32 v8, v165, v8
	v_mul_f32_e32 v9, v165, v9
	v_mul_f32_e32 v10, v165, v10
	v_mul_f32_e32 v11, v165, v11
	v_mul_f32_e32 v12, v165, v12
	v_mul_f32_e32 v13, v165, v13
	v_mul_f32_e32 v14, v165, v14
	v_mul_f32_e32 v15, v165, v15
	v_mul_f32_e32 v16, v165, v16
	v_mul_f32_e32 v17, v165, v17
	v_mul_f32_e32 v18, v165, v18
	v_mul_f32_e32 v19, v165, v19
	v_mul_f32_e32 v20, v165, v20
	v_mul_f32_e32 v21, v165, v21
	v_mul_f32_e32 v22, v165, v22
	v_mul_f32_e32 v23, v165, v23
	v_mul_f32_e32 v24, v165, v24
	v_mul_f32_e32 v25, v165, v25
	v_mul_f32_e32 v26, v165, v26
	v_mul_f32_e32 v27, v165, v27
	v_mul_f32_e32 v28, v165, v28
	v_mul_f32_e32 v29, v165, v29
	v_mul_f32_e32 v30, v165, v30
	v_mul_f32_e32 v31, v165, v31
.Lamoba_noscale:
	v_cvt_pk_bf16_f32 v162, v32, v33
	v_cvt_pk_bf16_f32 v163, v34, v35
	v_cvt_pk_bf16_f32 v164, v36, v37
	v_cvt_pk_bf16_f32 v165, v38, v39
	v_cvt_pk_bf16_f32 v166, v40, v41
	v_cvt_pk_bf16_f32 v167, v42, v43
	v_cvt_pk_bf16_f32 v168, v44, v45
	v_cvt_pk_bf16_f32 v169, v46, v47
	v_cvt_pk_bf16_f32 v170, v48, v49
	v_cvt_pk_bf16_f32 v171, v50, v51
	v_cvt_pk_bf16_f32 v172, v52, v53
	v_cvt_pk_bf16_f32 v173, v54, v55
	v_cvt_pk_bf16_f32 v174, v56, v57
	v_cvt_pk_bf16_f32 v175, v58, v59
	v_cvt_pk_bf16_f32 v176, v60, v61
	v_cvt_pk_bf16_f32 v177, v62, v63
	s_waitcnt lgkmcnt(0)
	s_nop 1
	v_mfma_f32_32x32x16_bf16 v[0:15], v[64:67], v[162:165], v[0:15]
	v_mfma_f32_32x32x16_bf16 v[16:31], v[68:71], v[162:165], v[16:31]
	v_mfma_f32_32x32x16_bf16 v[0:15], v[72:75], v[166:169], v[0:15]
	v_mfma_f32_32x32x16_bf16 v[16:31], v[76:79], v[166:169], v[16:31]
	v_mfma_f32_32x32x16_bf16 v[0:15], v[138:141], v[170:173], v[0:15]
	v_mfma_f32_32x32x16_bf16 v[16:31], v[142:145], v[170:173], v[16:31]
	v_mfma_f32_32x32x16_bf16 v[0:15], v[146:149], v[174:177], v[0:15]
	v_mfma_f32_32x32x16_bf16 v[16:31], v[150:153], v[174:177], v[16:31]
	s_branch .Lamoba_skip
.Lamoba_skip0:
	s_lshr_b32 s24, s59, 1
	s_min_u32 s24, s23, s24
	s_lshl_b32 s26, s24, 13
	s_lshl_b32 s24, s58, 10
	s_add_u32 s26, s26, s24
	s_mov_b32 s27, 0
	v_lshl_add_u64 v[186:187], v[134:135], 0, s[26:27]
	v_lshl_add_u64 v[218:219], v[136:137], 0, s[26:27]
	v_add_co_u32_e32 v218, vcc, v218, v185
	v_addc_co_u32_e32 v219, vcc, 0, v219, vcc
	s_add_u32 s24, s24, s62
	s_mov_b32 m0, s24
	s_nop 0
	global_load_lds_dwordx4 v[186:187], off
	s_add_u32 s24, s24, 0x2000
	s_mov_b32 m0, s24
	s_nop 0
	global_load_lds_dwordx4 v[218:219], off
